# rms-norm GEMM epilogue row loops (odin Q/K, evin Q/Kslc/Kwin) rewritten: all 32 row sums of squares first with two lanes per row and packed fma, one rsqrt, rows scaled with the factor from v_readlane;
# speedup vs baseline: 1.0007x; 1.0007x over previous
.LBB0_491:
	v_and_b32_e32 v183, 63, v208
	v_lshlrev_b32_e32 v182, 3, v183
	v_sub_u32_e32 v182, v134, v182
	v_lshrrev_b32_e32 v184, 1, v183
	v_and_b32_e32 v183, 1, v183
	v_mul_u32_u24_e32 v184, 0x204, v184
	v_lshl_add_u32 v184, v183, 8, v184
	v_add_u32_e32 v182, v182, v184
	v_mov_b32_e32 v178, 0
	v_mov_b32_e32 v179, 0
	v_mov_b32_e32 v180, 0
	v_mov_b32_e32 v181, 0
	ds_read2_b32 v[222:223], v182 offset0:0 offset1:1
	ds_read2_b32 v[224:225], v182 offset0:2 offset1:3
	ds_read2_b32 v[226:227], v182 offset0:4 offset1:5
	ds_read2_b32 v[228:229], v182 offset0:6 offset1:7
	ds_read2_b32 v[230:231], v182 offset0:8 offset1:9
	ds_read2_b32 v[232:233], v182 offset0:10 offset1:11
	ds_read2_b32 v[234:235], v182 offset0:12 offset1:13
	ds_read2_b32 v[236:237], v182 offset0:14 offset1:15
	ds_read2_b32 v[238:239], v182 offset0:16 offset1:17
	ds_read2_b32 v[240:241], v182 offset0:18 offset1:19
	ds_read2_b32 v[242:243], v182 offset0:20 offset1:21
	ds_read2_b32 v[244:245], v182 offset0:22 offset1:23
	s_waitcnt lgkmcnt(11)
	v_pk_fma_f32 v[178:179], v[222:223], v[222:223], v[178:179]
	ds_read2_b32 v[246:247], v182 offset0:24 offset1:25
	s_waitcnt lgkmcnt(11)
	v_pk_fma_f32 v[180:181], v[224:225], v[224:225], v[180:181]
	ds_read2_b32 v[248:249], v182 offset0:26 offset1:27
	s_waitcnt lgkmcnt(11)
	v_pk_fma_f32 v[178:179], v[226:227], v[226:227], v[178:179]
	ds_read2_b32 v[250:251], v182 offset0:28 offset1:29
	s_waitcnt lgkmcnt(11)
	v_pk_fma_f32 v[180:181], v[228:229], v[228:229], v[180:181]
	ds_read2_b32 v[252:253], v182 offset0:30 offset1:31
	s_waitcnt lgkmcnt(11)
	v_pk_fma_f32 v[178:179], v[230:231], v[230:231], v[178:179]
	ds_read2_b32 v[222:223], v182 offset0:32 offset1:33
	s_waitcnt lgkmcnt(11)
	v_pk_fma_f32 v[180:181], v[232:233], v[232:233], v[180:181]
	ds_read2_b32 v[224:225], v182 offset0:34 offset1:35
	s_waitcnt lgkmcnt(11)
	v_pk_fma_f32 v[178:179], v[234:235], v[234:235], v[178:179]
	ds_read2_b32 v[226:227], v182 offset0:36 offset1:37
	s_waitcnt lgkmcnt(11)
	v_pk_fma_f32 v[180:181], v[236:237], v[236:237], v[180:181]
	ds_read2_b32 v[228:229], v182 offset0:38 offset1:39
	s_waitcnt lgkmcnt(11)
	v_pk_fma_f32 v[178:179], v[238:239], v[238:239], v[178:179]
	ds_read2_b32 v[230:231], v182 offset0:40 offset1:41
	s_waitcnt lgkmcnt(11)
	v_pk_fma_f32 v[180:181], v[240:241], v[240:241], v[180:181]
	ds_read2_b32 v[232:233], v182 offset0:42 offset1:43
	s_waitcnt lgkmcnt(11)
	v_pk_fma_f32 v[178:179], v[242:243], v[242:243], v[178:179]
	ds_read2_b32 v[234:235], v182 offset0:44 offset1:45
	s_waitcnt lgkmcnt(11)
	v_pk_fma_f32 v[180:181], v[244:245], v[244:245], v[180:181]
	ds_read2_b32 v[236:237], v182 offset0:46 offset1:47
	s_waitcnt lgkmcnt(11)
	v_pk_fma_f32 v[178:179], v[246:247], v[246:247], v[178:179]
	ds_read2_b32 v[238:239], v182 offset0:48 offset1:49
	s_waitcnt lgkmcnt(11)
	v_pk_fma_f32 v[180:181], v[248:249], v[248:249], v[180:181]
	ds_read2_b32 v[240:241], v182 offset0:50 offset1:51
	s_waitcnt lgkmcnt(11)
	v_pk_fma_f32 v[178:179], v[250:251], v[250:251], v[178:179]
	ds_read2_b32 v[242:243], v182 offset0:52 offset1:53
	s_waitcnt lgkmcnt(11)
	v_pk_fma_f32 v[180:181], v[252:253], v[252:253], v[180:181]
	ds_read2_b32 v[244:245], v182 offset0:54 offset1:55
	s_waitcnt lgkmcnt(11)
	v_pk_fma_f32 v[178:179], v[222:223], v[222:223], v[178:179]
	ds_read2_b32 v[246:247], v182 offset0:56 offset1:57
	s_waitcnt lgkmcnt(11)
	v_pk_fma_f32 v[180:181], v[224:225], v[224:225], v[180:181]
	ds_read2_b32 v[248:249], v182 offset0:58 offset1:59
	s_waitcnt lgkmcnt(11)
	v_pk_fma_f32 v[178:179], v[226:227], v[226:227], v[178:179]
	ds_read2_b32 v[250:251], v182 offset0:60 offset1:61
	s_waitcnt lgkmcnt(11)
	v_pk_fma_f32 v[180:181], v[228:229], v[228:229], v[180:181]
	ds_read2_b32 v[252:253], v182 offset0:62 offset1:63
	s_waitcnt lgkmcnt(11)
	v_pk_fma_f32 v[178:179], v[230:231], v[230:231], v[178:179]
	s_waitcnt lgkmcnt(10)
	v_pk_fma_f32 v[180:181], v[232:233], v[232:233], v[180:181]
	s_waitcnt lgkmcnt(9)
	v_pk_fma_f32 v[178:179], v[234:235], v[234:235], v[178:179]
	s_waitcnt lgkmcnt(8)
	v_pk_fma_f32 v[180:181], v[236:237], v[236:237], v[180:181]
	s_waitcnt lgkmcnt(7)
	v_pk_fma_f32 v[178:179], v[238:239], v[238:239], v[178:179]
	s_waitcnt lgkmcnt(6)
	v_pk_fma_f32 v[180:181], v[240:241], v[240:241], v[180:181]
	s_waitcnt lgkmcnt(5)
	v_pk_fma_f32 v[178:179], v[242:243], v[242:243], v[178:179]
	s_waitcnt lgkmcnt(4)
	v_pk_fma_f32 v[180:181], v[244:245], v[244:245], v[180:181]
	s_waitcnt lgkmcnt(3)
	v_pk_fma_f32 v[178:179], v[246:247], v[246:247], v[178:179]
	s_waitcnt lgkmcnt(2)
	v_pk_fma_f32 v[180:181], v[248:249], v[248:249], v[180:181]
	s_waitcnt lgkmcnt(1)
	v_pk_fma_f32 v[178:179], v[250:251], v[250:251], v[178:179]
	s_waitcnt lgkmcnt(0)
	v_pk_fma_f32 v[180:181], v[252:253], v[252:253], v[180:181]
	s_nop 0
	v_pk_add_f32 v[178:179], v[178:179], v[180:181]
	s_nop 0
	v_add_f32_e32 v178, v178, v179
	s_nop 1
	v_add_f32_dpp v178, v178, v178 quad_perm:[1,0,3,2] row_mask:0xf bank_mask:0xf bound_ctrl:1
	v_fmamk_f32 v178, v178, 0x3c000000, v209
	v_mul_f32_e32 v179, 0x4b800000, v178
	v_cmp_gt_f32_e32 vcc, s52, v178
	s_nop 1
	v_cndmask_b32_e32 v178, v178, v179, vcc
	v_rsq_f32_e32 v178, v178
	s_nop 0
	v_mul_f32_e32 v179, 0x45800000, v178
	v_cndmask_b32_e32 v178, v178, v179, vcc
	v_mov_b32_e32 v185, v134
	ds_read2_b32 v[186:187], v185 offset1:1
	ds_read2_b32 v[188:189], v185 offset0:129 offset1:130
	v_add_u32_e32 v185, 0x408, v185
	ds_read2_b32 v[190:191], v185 offset1:1
	ds_read2_b32 v[192:193], v185 offset0:129 offset1:130
	v_add_u32_e32 v185, 0x408, v185
	s_nop 0
	v_readlane_b32 s4, v178, 0
	v_readlane_b32 s100, v178, 2
	ds_read2_b32 v[194:195], v185 offset1:1
	ds_read2_b32 v[196:197], v185 offset0:129 offset1:130
	v_add_u32_e32 v185, 0x408, v185
	s_waitcnt lgkmcnt(4)
	v_pk_mul_f32 v[186:187], v[186:187], s[4:5] op_sel_hi:[1,0]
	v_pk_mul_f32 v[188:189], v[188:189], s[100:101] op_sel_hi:[1,0]
	v_readlane_b32 vcc_lo, v178, 4
	v_readlane_b32 s4, v178, 6
	v_pk_mul_f32 v[186:187], v[130:131], v[186:187]
	v_pk_mul_f32 v[188:189], v[130:131], v[188:189]
	v_cvt_pk_bf16_f32 v202, v186, v187
	v_cvt_pk_bf16_f32 v203, v188, v189
	global_store_dword v[132:133], v202, off
	v_lshl_add_u64 v[132:133], v[132:133], 0, s[82:83]
	global_store_dword v[132:133], v203, off
	v_lshl_add_u64 v[132:133], v[132:133], 0, s[82:83]
	ds_read2_b32 v[198:199], v185 offset1:1
	ds_read2_b32 v[200:201], v185 offset0:129 offset1:130
	v_add_u32_e32 v185, 0x408, v185
	s_waitcnt lgkmcnt(4)
	v_pk_mul_f32 v[190:191], v[190:191], vcc op_sel_hi:[1,0]
	v_pk_mul_f32 v[192:193], v[192:193], s[4:5] op_sel_hi:[1,0]
	v_readlane_b32 s100, v178, 8
	v_readlane_b32 vcc_lo, v178, 10
	v_pk_mul_f32 v[190:191], v[130:131], v[190:191]
	v_pk_mul_f32 v[192:193], v[130:131], v[192:193]
	v_cvt_pk_bf16_f32 v202, v190, v191
	v_cvt_pk_bf16_f32 v203, v192, v193
	global_store_dword v[132:133], v202, off
	v_lshl_add_u64 v[132:133], v[132:133], 0, s[82:83]
	global_store_dword v[132:133], v203, off
	v_lshl_add_u64 v[132:133], v[132:133], 0, s[82:83]
	ds_read2_b32 v[186:187], v185 offset1:1
	ds_read2_b32 v[188:189], v185 offset0:129 offset1:130
	v_add_u32_e32 v185, 0x408, v185
	s_waitcnt lgkmcnt(4)
	v_pk_mul_f32 v[194:195], v[194:195], s[100:101] op_sel_hi:[1,0]
	v_pk_mul_f32 v[196:197], v[196:197], vcc op_sel_hi:[1,0]
	v_readlane_b32 s4, v178, 12
	v_readlane_b32 s100, v178, 14
	v_pk_mul_f32 v[194:195], v[130:131], v[194:195]
	v_pk_mul_f32 v[196:197], v[130:131], v[196:197]
	v_cvt_pk_bf16_f32 v202, v194, v195
	v_cvt_pk_bf16_f32 v203, v196, v197
	global_store_dword v[132:133], v202, off
	v_lshl_add_u64 v[132:133], v[132:133], 0, s[82:83]
	global_store_dword v[132:133], v203, off
	v_lshl_add_u64 v[132:133], v[132:133], 0, s[82:83]
	ds_read2_b32 v[190:191], v185 offset1:1
	ds_read2_b32 v[192:193], v185 offset0:129 offset1:130
	v_add_u32_e32 v185, 0x408, v185
	s_waitcnt lgkmcnt(4)
	v_pk_mul_f32 v[198:199], v[198:199], s[4:5] op_sel_hi:[1,0]
	v_pk_mul_f32 v[200:201], v[200:201], s[100:101] op_sel_hi:[1,0]
	v_readlane_b32 vcc_lo, v178, 16
	v_readlane_b32 s4, v178, 18
	v_pk_mul_f32 v[198:199], v[130:131], v[198:199]
	v_pk_mul_f32 v[200:201], v[130:131], v[200:201]
	v_cvt_pk_bf16_f32 v202, v198, v199
	v_cvt_pk_bf16_f32 v203, v200, v201
	global_store_dword v[132:133], v202, off
	v_lshl_add_u64 v[132:133], v[132:133], 0, s[82:83]
	global_store_dword v[132:133], v203, off
	v_lshl_add_u64 v[132:133], v[132:133], 0, s[82:83]
	ds_read2_b32 v[194:195], v185 offset1:1
	ds_read2_b32 v[196:197], v185 offset0:129 offset1:130
	v_add_u32_e32 v185, 0x408, v185
	s_waitcnt lgkmcnt(4)
	v_pk_mul_f32 v[186:187], v[186:187], vcc op_sel_hi:[1,0]
	v_pk_mul_f32 v[188:189], v[188:189], s[4:5] op_sel_hi:[1,0]
	v_readlane_b32 s100, v178, 20
	v_readlane_b32 vcc_lo, v178, 22
	v_pk_mul_f32 v[186:187], v[130:131], v[186:187]
	v_pk_mul_f32 v[188:189], v[130:131], v[188:189]
	v_cvt_pk_bf16_f32 v202, v186, v187
	v_cvt_pk_bf16_f32 v203, v188, v189
	global_store_dword v[132:133], v202, off
	v_lshl_add_u64 v[132:133], v[132:133], 0, s[82:83]
	global_store_dword v[132:133], v203, off
	v_lshl_add_u64 v[132:133], v[132:133], 0, s[82:83]
	ds_read2_b32 v[198:199], v185 offset1:1
	ds_read2_b32 v[200:201], v185 offset0:129 offset1:130
	v_add_u32_e32 v185, 0x408, v185
	s_waitcnt lgkmcnt(4)
	v_pk_mul_f32 v[190:191], v[190:191], s[100:101] op_sel_hi:[1,0]
	v_pk_mul_f32 v[192:193], v[192:193], vcc op_sel_hi:[1,0]
	v_readlane_b32 s4, v178, 24
	v_readlane_b32 s100, v178, 26
	v_pk_mul_f32 v[190:191], v[130:131], v[190:191]
	v_pk_mul_f32 v[192:193], v[130:131], v[192:193]
	v_cvt_pk_bf16_f32 v202, v190, v191
	v_cvt_pk_bf16_f32 v203, v192, v193
	global_store_dword v[132:133], v202, off
	v_lshl_add_u64 v[132:133], v[132:133], 0, s[82:83]
	global_store_dword v[132:133], v203, off
	v_lshl_add_u64 v[132:133], v[132:133], 0, s[82:83]
	ds_read2_b32 v[186:187], v185 offset1:1
	ds_read2_b32 v[188:189], v185 offset0:129 offset1:130
	v_add_u32_e32 v185, 0x408, v185
	s_waitcnt lgkmcnt(4)
	v_pk_mul_f32 v[194:195], v[194:195], s[4:5] op_sel_hi:[1,0]
	v_pk_mul_f32 v[196:197], v[196:197], s[100:101] op_sel_hi:[1,0]
	v_readlane_b32 vcc_lo, v178, 28
	v_readlane_b32 s4, v178, 30
	v_pk_mul_f32 v[194:195], v[130:131], v[194:195]
	v_pk_mul_f32 v[196:197], v[130:131], v[196:197]
	v_cvt_pk_bf16_f32 v202, v194, v195
	v_cvt_pk_bf16_f32 v203, v196, v197
	global_store_dword v[132:133], v202, off
	v_lshl_add_u64 v[132:133], v[132:133], 0, s[82:83]
	global_store_dword v[132:133], v203, off
	v_lshl_add_u64 v[132:133], v[132:133], 0, s[82:83]
	ds_read2_b32 v[190:191], v185 offset1:1
	ds_read2_b32 v[192:193], v185 offset0:129 offset1:130
	v_add_u32_e32 v185, 0x408, v185
	s_waitcnt lgkmcnt(4)
	v_pk_mul_f32 v[198:199], v[198:199], vcc op_sel_hi:[1,0]
	v_pk_mul_f32 v[200:201], v[200:201], s[4:5] op_sel_hi:[1,0]
	v_readlane_b32 s100, v178, 32
	v_readlane_b32 vcc_lo, v178, 34
	v_pk_mul_f32 v[198:199], v[130:131], v[198:199]
	v_pk_mul_f32 v[200:201], v[130:131], v[200:201]
	v_cvt_pk_bf16_f32 v202, v198, v199
	v_cvt_pk_bf16_f32 v203, v200, v201
	global_store_dword v[132:133], v202, off
	v_lshl_add_u64 v[132:133], v[132:133], 0, s[82:83]
	global_store_dword v[132:133], v203, off
	v_lshl_add_u64 v[132:133], v[132:133], 0, s[82:83]
	ds_read2_b32 v[194:195], v185 offset1:1
	ds_read2_b32 v[196:197], v185 offset0:129 offset1:130
	v_add_u32_e32 v185, 0x408, v185
	s_waitcnt lgkmcnt(4)
	v_pk_mul_f32 v[186:187], v[186:187], s[100:101] op_sel_hi:[1,0]
	v_pk_mul_f32 v[188:189], v[188:189], vcc op_sel_hi:[1,0]
	v_readlane_b32 s4, v178, 36
	v_readlane_b32 s100, v178, 38
	v_pk_mul_f32 v[186:187], v[130:131], v[186:187]
	v_pk_mul_f32 v[188:189], v[130:131], v[188:189]
	v_cvt_pk_bf16_f32 v202, v186, v187
	v_cvt_pk_bf16_f32 v203, v188, v189
	global_store_dword v[132:133], v202, off
	v_lshl_add_u64 v[132:133], v[132:133], 0, s[82:83]
	global_store_dword v[132:133], v203, off
	v_lshl_add_u64 v[132:133], v[132:133], 0, s[82:83]
	ds_read2_b32 v[198:199], v185 offset1:1
	ds_read2_b32 v[200:201], v185 offset0:129 offset1:130
	v_add_u32_e32 v185, 0x408, v185
	s_waitcnt lgkmcnt(4)
	v_pk_mul_f32 v[190:191], v[190:191], s[4:5] op_sel_hi:[1,0]
	v_pk_mul_f32 v[192:193], v[192:193], s[100:101] op_sel_hi:[1,0]
	v_readlane_b32 vcc_lo, v178, 40
	v_readlane_b32 s4, v178, 42
	v_pk_mul_f32 v[190:191], v[130:131], v[190:191]
	v_pk_mul_f32 v[192:193], v[130:131], v[192:193]
	v_cvt_pk_bf16_f32 v202, v190, v191
	v_cvt_pk_bf16_f32 v203, v192, v193
	global_store_dword v[132:133], v202, off
	v_lshl_add_u64 v[132:133], v[132:133], 0, s[82:83]
	global_store_dword v[132:133], v203, off
	v_lshl_add_u64 v[132:133], v[132:133], 0, s[82:83]
	ds_read2_b32 v[186:187], v185 offset1:1
	ds_read2_b32 v[188:189], v185 offset0:129 offset1:130
	v_add_u32_e32 v185, 0x408, v185
	s_waitcnt lgkmcnt(4)
	v_pk_mul_f32 v[194:195], v[194:195], vcc op_sel_hi:[1,0]
	v_pk_mul_f32 v[196:197], v[196:197], s[4:5] op_sel_hi:[1,0]
	v_readlane_b32 s100, v178, 44
	v_readlane_b32 vcc_lo, v178, 46
	v_pk_mul_f32 v[194:195], v[130:131], v[194:195]
	v_pk_mul_f32 v[196:197], v[130:131], v[196:197]
	v_cvt_pk_bf16_f32 v202, v194, v195
	v_cvt_pk_bf16_f32 v203, v196, v197
	global_store_dword v[132:133], v202, off
	v_lshl_add_u64 v[132:133], v[132:133], 0, s[82:83]
	global_store_dword v[132:133], v203, off
	v_lshl_add_u64 v[132:133], v[132:133], 0, s[82:83]
	ds_read2_b32 v[190:191], v185 offset1:1
	ds_read2_b32 v[192:193], v185 offset0:129 offset1:130
	v_add_u32_e32 v185, 0x408, v185
	s_waitcnt lgkmcnt(4)
	v_pk_mul_f32 v[198:199], v[198:199], s[100:101] op_sel_hi:[1,0]
	v_pk_mul_f32 v[200:201], v[200:201], vcc op_sel_hi:[1,0]
	v_readlane_b32 s4, v178, 48
	v_readlane_b32 s100, v178, 50
	v_pk_mul_f32 v[198:199], v[130:131], v[198:199]
	v_pk_mul_f32 v[200:201], v[130:131], v[200:201]
	v_cvt_pk_bf16_f32 v202, v198, v199
	v_cvt_pk_bf16_f32 v203, v200, v201
	global_store_dword v[132:133], v202, off
	v_lshl_add_u64 v[132:133], v[132:133], 0, s[82:83]
	global_store_dword v[132:133], v203, off
	v_lshl_add_u64 v[132:133], v[132:133], 0, s[82:83]
	ds_read2_b32 v[194:195], v185 offset1:1
	ds_read2_b32 v[196:197], v185 offset0:129 offset1:130
	v_add_u32_e32 v185, 0x408, v185
	s_waitcnt lgkmcnt(4)
	v_pk_mul_f32 v[186:187], v[186:187], s[4:5] op_sel_hi:[1,0]
	v_pk_mul_f32 v[188:189], v[188:189], s[100:101] op_sel_hi:[1,0]
	v_readlane_b32 vcc_lo, v178, 52
	v_readlane_b32 s4, v178, 54
	v_pk_mul_f32 v[186:187], v[130:131], v[186:187]
	v_pk_mul_f32 v[188:189], v[130:131], v[188:189]
	v_cvt_pk_bf16_f32 v202, v186, v187
	v_cvt_pk_bf16_f32 v203, v188, v189
	global_store_dword v[132:133], v202, off
	v_lshl_add_u64 v[132:133], v[132:133], 0, s[82:83]
	global_store_dword v[132:133], v203, off
	v_lshl_add_u64 v[132:133], v[132:133], 0, s[82:83]
	ds_read2_b32 v[198:199], v185 offset1:1
	ds_read2_b32 v[200:201], v185 offset0:129 offset1:130
	v_add_u32_e32 v185, 0x408, v185
	s_waitcnt lgkmcnt(4)
	v_pk_mul_f32 v[190:191], v[190:191], vcc op_sel_hi:[1,0]
	v_pk_mul_f32 v[192:193], v[192:193], s[4:5] op_sel_hi:[1,0]
	v_readlane_b32 s100, v178, 56
	v_readlane_b32 vcc_lo, v178, 58
	v_pk_mul_f32 v[190:191], v[130:131], v[190:191]
	v_pk_mul_f32 v[192:193], v[130:131], v[192:193]
	v_cvt_pk_bf16_f32 v202, v190, v191
	v_cvt_pk_bf16_f32 v203, v192, v193
	global_store_dword v[132:133], v202, off
	v_lshl_add_u64 v[132:133], v[132:133], 0, s[82:83]
	global_store_dword v[132:133], v203, off
	v_lshl_add_u64 v[132:133], v[132:133], 0, s[82:83]
	s_waitcnt lgkmcnt(2)
	v_pk_mul_f32 v[194:195], v[194:195], s[100:101] op_sel_hi:[1,0]
	v_pk_mul_f32 v[196:197], v[196:197], vcc op_sel_hi:[1,0]
	v_readlane_b32 s4, v178, 60
	v_readlane_b32 s100, v178, 62
	v_pk_mul_f32 v[194:195], v[130:131], v[194:195]
	v_pk_mul_f32 v[196:197], v[130:131], v[196:197]
	v_cvt_pk_bf16_f32 v202, v194, v195
	v_cvt_pk_bf16_f32 v203, v196, v197
	global_store_dword v[132:133], v202, off
	v_lshl_add_u64 v[132:133], v[132:133], 0, s[82:83]
	global_store_dword v[132:133], v203, off
	v_lshl_add_u64 v[132:133], v[132:133], 0, s[82:83]
	s_waitcnt lgkmcnt(0)
	v_pk_mul_f32 v[198:199], v[198:199], s[4:5] op_sel_hi:[1,0]
	v_pk_mul_f32 v[200:201], v[200:201], s[100:101] op_sel_hi:[1,0]
	s_nop 1
	v_pk_mul_f32 v[198:199], v[130:131], v[198:199]
	v_pk_mul_f32 v[200:201], v[130:131], v[200:201]
	v_cvt_pk_bf16_f32 v202, v198, v199
	v_cvt_pk_bf16_f32 v203, v200, v201
	global_store_dword v[132:133], v202, off
	v_lshl_add_u64 v[132:133], v[132:133], 0, s[82:83]
	global_store_dword v[132:133], v203, off
	v_lshl_add_u64 v[132:133], v[132:133], 0, s[82:83]
	s_movk_i32 s4, 0x4080

.LBB0_495:
	v_and_b32_e32 v183, 63, v208
	v_lshlrev_b32_e32 v182, 3, v183
	v_sub_u32_e32 v182, v134, v182
	v_lshrrev_b32_e32 v184, 1, v183
	v_and_b32_e32 v183, 1, v183
	v_mul_u32_u24_e32 v184, 0x204, v184
	v_lshl_add_u32 v184, v183, 8, v184
	v_add_u32_e32 v182, v182, v184
	v_mov_b32_e32 v178, 0
	v_mov_b32_e32 v179, 0
	v_mov_b32_e32 v180, 0
	v_mov_b32_e32 v181, 0
	ds_read2_b32 v[222:223], v182 offset0:0 offset1:1
	ds_read2_b32 v[224:225], v182 offset0:2 offset1:3
	ds_read2_b32 v[226:227], v182 offset0:4 offset1:5
	ds_read2_b32 v[228:229], v182 offset0:6 offset1:7
	ds_read2_b32 v[230:231], v182 offset0:8 offset1:9
	ds_read2_b32 v[232:233], v182 offset0:10 offset1:11
	ds_read2_b32 v[234:235], v182 offset0:12 offset1:13
	ds_read2_b32 v[236:237], v182 offset0:14 offset1:15
	ds_read2_b32 v[238:239], v182 offset0:16 offset1:17
	ds_read2_b32 v[240:241], v182 offset0:18 offset1:19
	ds_read2_b32 v[242:243], v182 offset0:20 offset1:21
	ds_read2_b32 v[244:245], v182 offset0:22 offset1:23
	s_waitcnt lgkmcnt(11)
	v_pk_fma_f32 v[178:179], v[222:223], v[222:223], v[178:179]
	ds_read2_b32 v[246:247], v182 offset0:24 offset1:25
	s_waitcnt lgkmcnt(11)
	v_pk_fma_f32 v[180:181], v[224:225], v[224:225], v[180:181]
	ds_read2_b32 v[248:249], v182 offset0:26 offset1:27
	s_waitcnt lgkmcnt(11)
	v_pk_fma_f32 v[178:179], v[226:227], v[226:227], v[178:179]
	ds_read2_b32 v[250:251], v182 offset0:28 offset1:29
	s_waitcnt lgkmcnt(11)
	v_pk_fma_f32 v[180:181], v[228:229], v[228:229], v[180:181]
	ds_read2_b32 v[252:253], v182 offset0:30 offset1:31
	s_waitcnt lgkmcnt(11)
	v_pk_fma_f32 v[178:179], v[230:231], v[230:231], v[178:179]
	ds_read2_b32 v[222:223], v182 offset0:32 offset1:33
	s_waitcnt lgkmcnt(11)
	v_pk_fma_f32 v[180:181], v[232:233], v[232:233], v[180:181]
	ds_read2_b32 v[224:225], v182 offset0:34 offset1:35
	s_waitcnt lgkmcnt(11)
	v_pk_fma_f32 v[178:179], v[234:235], v[234:235], v[178:179]
	ds_read2_b32 v[226:227], v182 offset0:36 offset1:37
	s_waitcnt lgkmcnt(11)
	v_pk_fma_f32 v[180:181], v[236:237], v[236:237], v[180:181]
	ds_read2_b32 v[228:229], v182 offset0:38 offset1:39
	s_waitcnt lgkmcnt(11)
	v_pk_fma_f32 v[178:179], v[238:239], v[238:239], v[178:179]
	ds_read2_b32 v[230:231], v182 offset0:40 offset1:41
	s_waitcnt lgkmcnt(11)
	v_pk_fma_f32 v[180:181], v[240:241], v[240:241], v[180:181]
	ds_read2_b32 v[232:233], v182 offset0:42 offset1:43
	s_waitcnt lgkmcnt(11)
	v_pk_fma_f32 v[178:179], v[242:243], v[242:243], v[178:179]
	ds_read2_b32 v[234:235], v182 offset0:44 offset1:45
	s_waitcnt lgkmcnt(11)
	v_pk_fma_f32 v[180:181], v[244:245], v[244:245], v[180:181]
	ds_read2_b32 v[236:237], v182 offset0:46 offset1:47
	s_waitcnt lgkmcnt(11)
	v_pk_fma_f32 v[178:179], v[246:247], v[246:247], v[178:179]
	ds_read2_b32 v[238:239], v182 offset0:48 offset1:49
	s_waitcnt lgkmcnt(11)
	v_pk_fma_f32 v[180:181], v[248:249], v[248:249], v[180:181]
	ds_read2_b32 v[240:241], v182 offset0:50 offset1:51
	s_waitcnt lgkmcnt(11)
	v_pk_fma_f32 v[178:179], v[250:251], v[250:251], v[178:179]
	ds_read2_b32 v[242:243], v182 offset0:52 offset1:53
	s_waitcnt lgkmcnt(11)
	v_pk_fma_f32 v[180:181], v[252:253], v[252:253], v[180:181]
	ds_read2_b32 v[244:245], v182 offset0:54 offset1:55
	s_waitcnt lgkmcnt(11)
	v_pk_fma_f32 v[178:179], v[222:223], v[222:223], v[178:179]
	ds_read2_b32 v[246:247], v182 offset0:56 offset1:57
	s_waitcnt lgkmcnt(11)
	v_pk_fma_f32 v[180:181], v[224:225], v[224:225], v[180:181]
	ds_read2_b32 v[248:249], v182 offset0:58 offset1:59
	s_waitcnt lgkmcnt(11)
	v_pk_fma_f32 v[178:179], v[226:227], v[226:227], v[178:179]
	ds_read2_b32 v[250:251], v182 offset0:60 offset1:61
	s_waitcnt lgkmcnt(11)
	v_pk_fma_f32 v[180:181], v[228:229], v[228:229], v[180:181]
	ds_read2_b32 v[252:253], v182 offset0:62 offset1:63
	s_waitcnt lgkmcnt(11)
	v_pk_fma_f32 v[178:179], v[230:231], v[230:231], v[178:179]
	s_waitcnt lgkmcnt(10)
	v_pk_fma_f32 v[180:181], v[232:233], v[232:233], v[180:181]
	s_waitcnt lgkmcnt(9)
	v_pk_fma_f32 v[178:179], v[234:235], v[234:235], v[178:179]
	s_waitcnt lgkmcnt(8)
	v_pk_fma_f32 v[180:181], v[236:237], v[236:237], v[180:181]
	s_waitcnt lgkmcnt(7)
	v_pk_fma_f32 v[178:179], v[238:239], v[238:239], v[178:179]
	s_waitcnt lgkmcnt(6)
	v_pk_fma_f32 v[180:181], v[240:241], v[240:241], v[180:181]
	s_waitcnt lgkmcnt(5)
	v_pk_fma_f32 v[178:179], v[242:243], v[242:243], v[178:179]
	s_waitcnt lgkmcnt(4)
	v_pk_fma_f32 v[180:181], v[244:245], v[244:245], v[180:181]
	s_waitcnt lgkmcnt(3)
	v_pk_fma_f32 v[178:179], v[246:247], v[246:247], v[178:179]
	s_waitcnt lgkmcnt(2)
	v_pk_fma_f32 v[180:181], v[248:249], v[248:249], v[180:181]
	s_waitcnt lgkmcnt(1)
	v_pk_fma_f32 v[178:179], v[250:251], v[250:251], v[178:179]
	s_waitcnt lgkmcnt(0)
	v_pk_fma_f32 v[180:181], v[252:253], v[252:253], v[180:181]
	s_nop 0
	v_pk_add_f32 v[178:179], v[178:179], v[180:181]
	s_nop 0
	v_add_f32_e32 v178, v178, v179
	s_nop 1
	v_add_f32_dpp v178, v178, v178 quad_perm:[1,0,3,2] row_mask:0xf bank_mask:0xf bound_ctrl:1
	v_fmamk_f32 v178, v178, 0x3c000000, v209
	v_mul_f32_e32 v179, 0x4b800000, v178
	v_cmp_gt_f32_e32 vcc, s52, v178
	s_nop 1
	v_cndmask_b32_e32 v178, v178, v179, vcc
	v_rsq_f32_e32 v178, v178
	s_nop 0
	v_mul_f32_e32 v179, 0x45800000, v178
	v_cndmask_b32_e32 v178, v178, v179, vcc
	v_mov_b32_e32 v185, v134
	ds_read2_b32 v[186:187], v185 offset1:1
	ds_read2_b32 v[188:189], v185 offset0:129 offset1:130
	v_add_u32_e32 v185, 0x408, v185
	ds_read2_b32 v[190:191], v185 offset1:1
	ds_read2_b32 v[192:193], v185 offset0:129 offset1:130
	v_add_u32_e32 v185, 0x408, v185
	s_nop 0
	v_readlane_b32 s4, v178, 0
	v_readlane_b32 s100, v178, 2
	ds_read2_b32 v[194:195], v185 offset1:1
	ds_read2_b32 v[196:197], v185 offset0:129 offset1:130
	v_add_u32_e32 v185, 0x408, v185
	s_waitcnt lgkmcnt(4)
	v_pk_mul_f32 v[186:187], v[186:187], s[4:5] op_sel_hi:[1,0]
	v_pk_mul_f32 v[188:189], v[188:189], s[100:101] op_sel_hi:[1,0]
	v_readlane_b32 vcc_lo, v178, 4
	v_readlane_b32 s4, v178, 6
	v_pk_mul_f32 v[186:187], v[130:131], v[186:187]
	v_pk_mul_f32 v[188:189], v[130:131], v[188:189]
	v_cvt_pk_bf16_f32 v202, v186, v187
	v_cvt_pk_bf16_f32 v203, v188, v189
	global_store_dword v[132:133], v202, off
	v_lshl_add_u64 v[132:133], v[132:133], 0, s[82:83]
	global_store_dword v[132:133], v203, off
	v_lshl_add_u64 v[132:133], v[132:133], 0, s[82:83]
	ds_read2_b32 v[198:199], v185 offset1:1
	ds_read2_b32 v[200:201], v185 offset0:129 offset1:130
	v_add_u32_e32 v185, 0x408, v185
	s_waitcnt lgkmcnt(4)
	v_pk_mul_f32 v[190:191], v[190:191], vcc op_sel_hi:[1,0]
	v_pk_mul_f32 v[192:193], v[192:193], s[4:5] op_sel_hi:[1,0]
	v_readlane_b32 s100, v178, 8
	v_readlane_b32 vcc_lo, v178, 10
	v_pk_mul_f32 v[190:191], v[130:131], v[190:191]
	v_pk_mul_f32 v[192:193], v[130:131], v[192:193]
	v_cvt_pk_bf16_f32 v202, v190, v191
	v_cvt_pk_bf16_f32 v203, v192, v193
	global_store_dword v[132:133], v202, off
	v_lshl_add_u64 v[132:133], v[132:133], 0, s[82:83]
	global_store_dword v[132:133], v203, off
	v_lshl_add_u64 v[132:133], v[132:133], 0, s[82:83]
	ds_read2_b32 v[186:187], v185 offset1:1
	ds_read2_b32 v[188:189], v185 offset0:129 offset1:130
	v_add_u32_e32 v185, 0x408, v185
	s_waitcnt lgkmcnt(4)
	v_pk_mul_f32 v[194:195], v[194:195], s[100:101] op_sel_hi:[1,0]
	v_pk_mul_f32 v[196:197], v[196:197], vcc op_sel_hi:[1,0]
	v_readlane_b32 s4, v178, 12
	v_readlane_b32 s100, v178, 14
	v_pk_mul_f32 v[194:195], v[130:131], v[194:195]
	v_pk_mul_f32 v[196:197], v[130:131], v[196:197]
	v_cvt_pk_bf16_f32 v202, v194, v195
	v_cvt_pk_bf16_f32 v203, v196, v197
	global_store_dword v[132:133], v202, off
	v_lshl_add_u64 v[132:133], v[132:133], 0, s[82:83]
	global_store_dword v[132:133], v203, off
	v_lshl_add_u64 v[132:133], v[132:133], 0, s[82:83]
	ds_read2_b32 v[190:191], v185 offset1:1
	ds_read2_b32 v[192:193], v185 offset0:129 offset1:130
	v_add_u32_e32 v185, 0x408, v185
	s_waitcnt lgkmcnt(4)
	v_pk_mul_f32 v[198:199], v[198:199], s[4:5] op_sel_hi:[1,0]
	v_pk_mul_f32 v[200:201], v[200:201], s[100:101] op_sel_hi:[1,0]
	v_readlane_b32 vcc_lo, v178, 16
	v_readlane_b32 s4, v178, 18
	v_pk_mul_f32 v[198:199], v[130:131], v[198:199]
	v_pk_mul_f32 v[200:201], v[130:131], v[200:201]
	v_cvt_pk_bf16_f32 v202, v198, v199
	v_cvt_pk_bf16_f32 v203, v200, v201
	global_store_dword v[132:133], v202, off
	v_lshl_add_u64 v[132:133], v[132:133], 0, s[82:83]
	global_store_dword v[132:133], v203, off
	v_lshl_add_u64 v[132:133], v[132:133], 0, s[82:83]
	ds_read2_b32 v[194:195], v185 offset1:1
	ds_read2_b32 v[196:197], v185 offset0:129 offset1:130
	v_add_u32_e32 v185, 0x408, v185
	s_waitcnt lgkmcnt(4)
	v_pk_mul_f32 v[186:187], v[186:187], vcc op_sel_hi:[1,0]
	v_pk_mul_f32 v[188:189], v[188:189], s[4:5] op_sel_hi:[1,0]
	v_readlane_b32 s100, v178, 20
	v_readlane_b32 vcc_lo, v178, 22
	v_pk_mul_f32 v[186:187], v[130:131], v[186:187]
	v_pk_mul_f32 v[188:189], v[130:131], v[188:189]
	v_cvt_pk_bf16_f32 v202, v186, v187
	v_cvt_pk_bf16_f32 v203, v188, v189
	global_store_dword v[132:133], v202, off
	v_lshl_add_u64 v[132:133], v[132:133], 0, s[82:83]
	global_store_dword v[132:133], v203, off
	v_lshl_add_u64 v[132:133], v[132:133], 0, s[82:83]
	ds_read2_b32 v[198:199], v185 offset1:1
	ds_read2_b32 v[200:201], v185 offset0:129 offset1:130
	v_add_u32_e32 v185, 0x408, v185
	s_waitcnt lgkmcnt(4)
	v_pk_mul_f32 v[190:191], v[190:191], s[100:101] op_sel_hi:[1,0]
	v_pk_mul_f32 v[192:193], v[192:193], vcc op_sel_hi:[1,0]
	v_readlane_b32 s4, v178, 24
	v_readlane_b32 s100, v178, 26
	v_pk_mul_f32 v[190:191], v[130:131], v[190:191]
	v_pk_mul_f32 v[192:193], v[130:131], v[192:193]
	v_cvt_pk_bf16_f32 v202, v190, v191
	v_cvt_pk_bf16_f32 v203, v192, v193
	global_store_dword v[132:133], v202, off
	v_lshl_add_u64 v[132:133], v[132:133], 0, s[82:83]
	global_store_dword v[132:133], v203, off
	v_lshl_add_u64 v[132:133], v[132:133], 0, s[82:83]
	ds_read2_b32 v[186:187], v185 offset1:1
	ds_read2_b32 v[188:189], v185 offset0:129 offset1:130
	v_add_u32_e32 v185, 0x408, v185
	s_waitcnt lgkmcnt(4)
	v_pk_mul_f32 v[194:195], v[194:195], s[4:5] op_sel_hi:[1,0]
	v_pk_mul_f32 v[196:197], v[196:197], s[100:101] op_sel_hi:[1,0]
	v_readlane_b32 vcc_lo, v178, 28
	v_readlane_b32 s4, v178, 30
	v_pk_mul_f32 v[194:195], v[130:131], v[194:195]
	v_pk_mul_f32 v[196:197], v[130:131], v[196:197]
	v_cvt_pk_bf16_f32 v202, v194, v195
	v_cvt_pk_bf16_f32 v203, v196, v197
	global_store_dword v[132:133], v202, off
	v_lshl_add_u64 v[132:133], v[132:133], 0, s[82:83]
	global_store_dword v[132:133], v203, off
	v_lshl_add_u64 v[132:133], v[132:133], 0, s[82:83]
	ds_read2_b32 v[190:191], v185 offset1:1
	ds_read2_b32 v[192:193], v185 offset0:129 offset1:130
	v_add_u32_e32 v185, 0x408, v185
	s_waitcnt lgkmcnt(4)
	v_pk_mul_f32 v[198:199], v[198:199], vcc op_sel_hi:[1,0]
	v_pk_mul_f32 v[200:201], v[200:201], s[4:5] op_sel_hi:[1,0]
	v_readlane_b32 s100, v178, 32
	v_readlane_b32 vcc_lo, v178, 34
	v_pk_mul_f32 v[198:199], v[130:131], v[198:199]
	v_pk_mul_f32 v[200:201], v[130:131], v[200:201]
	v_cvt_pk_bf16_f32 v202, v198, v199
	v_cvt_pk_bf16_f32 v203, v200, v201
	global_store_dword v[132:133], v202, off
	v_lshl_add_u64 v[132:133], v[132:133], 0, s[82:83]
	global_store_dword v[132:133], v203, off
	v_lshl_add_u64 v[132:133], v[132:133], 0, s[82:83]
	ds_read2_b32 v[194:195], v185 offset1:1
	ds_read2_b32 v[196:197], v185 offset0:129 offset1:130
	v_add_u32_e32 v185, 0x408, v185
	s_waitcnt lgkmcnt(4)
	v_pk_mul_f32 v[186:187], v[186:187], s[100:101] op_sel_hi:[1,0]
	v_pk_mul_f32 v[188:189], v[188:189], vcc op_sel_hi:[1,0]
	v_readlane_b32 s4, v178, 36
	v_readlane_b32 s100, v178, 38
	v_pk_mul_f32 v[186:187], v[130:131], v[186:187]
	v_pk_mul_f32 v[188:189], v[130:131], v[188:189]
	v_cvt_pk_bf16_f32 v202, v186, v187
	v_cvt_pk_bf16_f32 v203, v188, v189
	global_store_dword v[132:133], v202, off
	v_lshl_add_u64 v[132:133], v[132:133], 0, s[82:83]
	global_store_dword v[132:133], v203, off
	v_lshl_add_u64 v[132:133], v[132:133], 0, s[82:83]
	ds_read2_b32 v[198:199], v185 offset1:1
	ds_read2_b32 v[200:201], v185 offset0:129 offset1:130
	v_add_u32_e32 v185, 0x408, v185
	s_waitcnt lgkmcnt(4)
	v_pk_mul_f32 v[190:191], v[190:191], s[4:5] op_sel_hi:[1,0]
	v_pk_mul_f32 v[192:193], v[192:193], s[100:101] op_sel_hi:[1,0]
	v_readlane_b32 vcc_lo, v178, 40
	v_readlane_b32 s4, v178, 42
	v_pk_mul_f32 v[190:191], v[130:131], v[190:191]
	v_pk_mul_f32 v[192:193], v[130:131], v[192:193]
	v_cvt_pk_bf16_f32 v202, v190, v191
	v_cvt_pk_bf16_f32 v203, v192, v193
	global_store_dword v[132:133], v202, off
	v_lshl_add_u64 v[132:133], v[132:133], 0, s[82:83]
	global_store_dword v[132:133], v203, off
	v_lshl_add_u64 v[132:133], v[132:133], 0, s[82:83]
	ds_read2_b32 v[186:187], v185 offset1:1
	ds_read2_b32 v[188:189], v185 offset0:129 offset1:130
	v_add_u32_e32 v185, 0x408, v185
	s_waitcnt lgkmcnt(4)
	v_pk_mul_f32 v[194:195], v[194:195], vcc op_sel_hi:[1,0]
	v_pk_mul_f32 v[196:197], v[196:197], s[4:5] op_sel_hi:[1,0]
	v_readlane_b32 s100, v178, 44
	v_readlane_b32 vcc_lo, v178, 46
	v_pk_mul_f32 v[194:195], v[130:131], v[194:195]
	v_pk_mul_f32 v[196:197], v[130:131], v[196:197]
	v_cvt_pk_bf16_f32 v202, v194, v195
	v_cvt_pk_bf16_f32 v203, v196, v197
	global_store_dword v[132:133], v202, off
	v_lshl_add_u64 v[132:133], v[132:133], 0, s[82:83]
	global_store_dword v[132:133], v203, off
	v_lshl_add_u64 v[132:133], v[132:133], 0, s[82:83]
	ds_read2_b32 v[190:191], v185 offset1:1
	ds_read2_b32 v[192:193], v185 offset0:129 offset1:130
	v_add_u32_e32 v185, 0x408, v185
	s_waitcnt lgkmcnt(4)
	v_pk_mul_f32 v[198:199], v[198:199], s[100:101] op_sel_hi:[1,0]
	v_pk_mul_f32 v[200:201], v[200:201], vcc op_sel_hi:[1,0]
	v_readlane_b32 s4, v178, 48
	v_readlane_b32 s100, v178, 50
	v_pk_mul_f32 v[198:199], v[130:131], v[198:199]
	v_pk_mul_f32 v[200:201], v[130:131], v[200:201]
	v_cvt_pk_bf16_f32 v202, v198, v199
	v_cvt_pk_bf16_f32 v203, v200, v201
	global_store_dword v[132:133], v202, off
	v_lshl_add_u64 v[132:133], v[132:133], 0, s[82:83]
	global_store_dword v[132:133], v203, off
	v_lshl_add_u64 v[132:133], v[132:133], 0, s[82:83]
	ds_read2_b32 v[194:195], v185 offset1:1
	ds_read2_b32 v[196:197], v185 offset0:129 offset1:130
	v_add_u32_e32 v185, 0x408, v185
	s_waitcnt lgkmcnt(4)
	v_pk_mul_f32 v[186:187], v[186:187], s[4:5] op_sel_hi:[1,0]
	v_pk_mul_f32 v[188:189], v[188:189], s[100:101] op_sel_hi:[1,0]
	v_readlane_b32 vcc_lo, v178, 52
	v_readlane_b32 s4, v178, 54
	v_pk_mul_f32 v[186:187], v[130:131], v[186:187]
	v_pk_mul_f32 v[188:189], v[130:131], v[188:189]
	v_cvt_pk_bf16_f32 v202, v186, v187
	v_cvt_pk_bf16_f32 v203, v188, v189
	global_store_dword v[132:133], v202, off
	v_lshl_add_u64 v[132:133], v[132:133], 0, s[82:83]
	global_store_dword v[132:133], v203, off
	v_lshl_add_u64 v[132:133], v[132:133], 0, s[82:83]
	ds_read2_b32 v[198:199], v185 offset1:1
	ds_read2_b32 v[200:201], v185 offset0:129 offset1:130
	v_add_u32_e32 v185, 0x408, v185
	s_waitcnt lgkmcnt(4)
	v_pk_mul_f32 v[190:191], v[190:191], vcc op_sel_hi:[1,0]
	v_pk_mul_f32 v[192:193], v[192:193], s[4:5] op_sel_hi:[1,0]
	v_readlane_b32 s100, v178, 56
	v_readlane_b32 vcc_lo, v178, 58
	v_pk_mul_f32 v[190:191], v[130:131], v[190:191]
	v_pk_mul_f32 v[192:193], v[130:131], v[192:193]
	v_cvt_pk_bf16_f32 v202, v190, v191
	v_cvt_pk_bf16_f32 v203, v192, v193
	global_store_dword v[132:133], v202, off
	v_lshl_add_u64 v[132:133], v[132:133], 0, s[82:83]
	global_store_dword v[132:133], v203, off
	v_lshl_add_u64 v[132:133], v[132:133], 0, s[82:83]
	s_waitcnt lgkmcnt(2)
	v_pk_mul_f32 v[194:195], v[194:195], s[100:101] op_sel_hi:[1,0]
	v_pk_mul_f32 v[196:197], v[196:197], vcc op_sel_hi:[1,0]
	v_readlane_b32 s4, v178, 60
	v_readlane_b32 s100, v178, 62
	v_pk_mul_f32 v[194:195], v[130:131], v[194:195]
	v_pk_mul_f32 v[196:197], v[130:131], v[196:197]
	v_cvt_pk_bf16_f32 v202, v194, v195
	v_cvt_pk_bf16_f32 v203, v196, v197
	global_store_dword v[132:133], v202, off
	v_lshl_add_u64 v[132:133], v[132:133], 0, s[82:83]
	global_store_dword v[132:133], v203, off
	v_lshl_add_u64 v[132:133], v[132:133], 0, s[82:83]
	s_waitcnt lgkmcnt(0)
	v_pk_mul_f32 v[198:199], v[198:199], s[4:5] op_sel_hi:[1,0]
	v_pk_mul_f32 v[200:201], v[200:201], s[100:101] op_sel_hi:[1,0]
	s_nop 1
	v_pk_mul_f32 v[198:199], v[130:131], v[198:199]
	v_pk_mul_f32 v[200:201], v[130:131], v[200:201]
	v_cvt_pk_bf16_f32 v202, v198, v199
	v_cvt_pk_bf16_f32 v203, v200, v201
	global_store_dword v[132:133], v202, off
	v_lshl_add_u64 v[132:133], v[132:133], 0, s[82:83]
	global_store_dword v[132:133], v203, off
	v_lshl_add_u64 v[132:133], v[132:133], 0, s[82:83]
	s_movk_i32 s4, 0x4080
	s_branch .LBB0_476

.LBB0_929:
	v_and_b32_e32 v183, 63, v208
	v_lshlrev_b32_e32 v182, 3, v183
	v_sub_u32_e32 v182, v134, v182
	v_lshrrev_b32_e32 v184, 1, v183
	v_and_b32_e32 v183, 1, v183
	v_mul_u32_u24_e32 v184, 0x204, v184
	v_lshl_add_u32 v184, v183, 8, v184
	v_add_u32_e32 v182, v182, v184
	v_mov_b32_e32 v178, 0
	v_mov_b32_e32 v179, 0
	v_mov_b32_e32 v180, 0
	v_mov_b32_e32 v181, 0
	ds_read2_b32 v[222:223], v182 offset0:0 offset1:1
	ds_read2_b32 v[224:225], v182 offset0:2 offset1:3
	ds_read2_b32 v[226:227], v182 offset0:4 offset1:5
	ds_read2_b32 v[228:229], v182 offset0:6 offset1:7
	ds_read2_b32 v[230:231], v182 offset0:8 offset1:9
	ds_read2_b32 v[232:233], v182 offset0:10 offset1:11
	ds_read2_b32 v[234:235], v182 offset0:12 offset1:13
	ds_read2_b32 v[236:237], v182 offset0:14 offset1:15
	ds_read2_b32 v[238:239], v182 offset0:16 offset1:17
	ds_read2_b32 v[240:241], v182 offset0:18 offset1:19
	ds_read2_b32 v[242:243], v182 offset0:20 offset1:21
	ds_read2_b32 v[244:245], v182 offset0:22 offset1:23
	s_waitcnt lgkmcnt(11)
	v_pk_fma_f32 v[178:179], v[222:223], v[222:223], v[178:179]
	ds_read2_b32 v[246:247], v182 offset0:24 offset1:25
	s_waitcnt lgkmcnt(11)
	v_pk_fma_f32 v[180:181], v[224:225], v[224:225], v[180:181]
	ds_read2_b32 v[248:249], v182 offset0:26 offset1:27
	s_waitcnt lgkmcnt(11)
	v_pk_fma_f32 v[178:179], v[226:227], v[226:227], v[178:179]
	ds_read2_b32 v[250:251], v182 offset0:28 offset1:29
	s_waitcnt lgkmcnt(11)
	v_pk_fma_f32 v[180:181], v[228:229], v[228:229], v[180:181]
	ds_read2_b32 v[252:253], v182 offset0:30 offset1:31
	s_waitcnt lgkmcnt(11)
	v_pk_fma_f32 v[178:179], v[230:231], v[230:231], v[178:179]
	ds_read2_b32 v[222:223], v182 offset0:32 offset1:33
	s_waitcnt lgkmcnt(11)
	v_pk_fma_f32 v[180:181], v[232:233], v[232:233], v[180:181]
	ds_read2_b32 v[224:225], v182 offset0:34 offset1:35
	s_waitcnt lgkmcnt(11)
	v_pk_fma_f32 v[178:179], v[234:235], v[234:235], v[178:179]
	ds_read2_b32 v[226:227], v182 offset0:36 offset1:37
	s_waitcnt lgkmcnt(11)
	v_pk_fma_f32 v[180:181], v[236:237], v[236:237], v[180:181]
	ds_read2_b32 v[228:229], v182 offset0:38 offset1:39
	s_waitcnt lgkmcnt(11)
	v_pk_fma_f32 v[178:179], v[238:239], v[238:239], v[178:179]
	ds_read2_b32 v[230:231], v182 offset0:40 offset1:41
	s_waitcnt lgkmcnt(11)
	v_pk_fma_f32 v[180:181], v[240:241], v[240:241], v[180:181]
	ds_read2_b32 v[232:233], v182 offset0:42 offset1:43
	s_waitcnt lgkmcnt(11)
	v_pk_fma_f32 v[178:179], v[242:243], v[242:243], v[178:179]
	ds_read2_b32 v[234:235], v182 offset0:44 offset1:45
	s_waitcnt lgkmcnt(11)
	v_pk_fma_f32 v[180:181], v[244:245], v[244:245], v[180:181]
	ds_read2_b32 v[236:237], v182 offset0:46 offset1:47
	s_waitcnt lgkmcnt(11)
	v_pk_fma_f32 v[178:179], v[246:247], v[246:247], v[178:179]
	ds_read2_b32 v[238:239], v182 offset0:48 offset1:49
	s_waitcnt lgkmcnt(11)
	v_pk_fma_f32 v[180:181], v[248:249], v[248:249], v[180:181]
	ds_read2_b32 v[240:241], v182 offset0:50 offset1:51
	s_waitcnt lgkmcnt(11)
	v_pk_fma_f32 v[178:179], v[250:251], v[250:251], v[178:179]
	ds_read2_b32 v[242:243], v182 offset0:52 offset1:53
	s_waitcnt lgkmcnt(11)
	v_pk_fma_f32 v[180:181], v[252:253], v[252:253], v[180:181]
	ds_read2_b32 v[244:245], v182 offset0:54 offset1:55
	s_waitcnt lgkmcnt(11)
	v_pk_fma_f32 v[178:179], v[222:223], v[222:223], v[178:179]
	ds_read2_b32 v[246:247], v182 offset0:56 offset1:57
	s_waitcnt lgkmcnt(11)
	v_pk_fma_f32 v[180:181], v[224:225], v[224:225], v[180:181]
	ds_read2_b32 v[248:249], v182 offset0:58 offset1:59
	s_waitcnt lgkmcnt(11)
	v_pk_fma_f32 v[178:179], v[226:227], v[226:227], v[178:179]
	ds_read2_b32 v[250:251], v182 offset0:60 offset1:61
	s_waitcnt lgkmcnt(11)
	v_pk_fma_f32 v[180:181], v[228:229], v[228:229], v[180:181]
	ds_read2_b32 v[252:253], v182 offset0:62 offset1:63
	s_waitcnt lgkmcnt(11)
	v_pk_fma_f32 v[178:179], v[230:231], v[230:231], v[178:179]
	s_waitcnt lgkmcnt(10)
	v_pk_fma_f32 v[180:181], v[232:233], v[232:233], v[180:181]
	s_waitcnt lgkmcnt(9)
	v_pk_fma_f32 v[178:179], v[234:235], v[234:235], v[178:179]
	s_waitcnt lgkmcnt(8)
	v_pk_fma_f32 v[180:181], v[236:237], v[236:237], v[180:181]
	s_waitcnt lgkmcnt(7)
	v_pk_fma_f32 v[178:179], v[238:239], v[238:239], v[178:179]
	s_waitcnt lgkmcnt(6)
	v_pk_fma_f32 v[180:181], v[240:241], v[240:241], v[180:181]
	s_waitcnt lgkmcnt(5)
	v_pk_fma_f32 v[178:179], v[242:243], v[242:243], v[178:179]
	s_waitcnt lgkmcnt(4)
	v_pk_fma_f32 v[180:181], v[244:245], v[244:245], v[180:181]
	s_waitcnt lgkmcnt(3)
	v_pk_fma_f32 v[178:179], v[246:247], v[246:247], v[178:179]
	s_waitcnt lgkmcnt(2)
	v_pk_fma_f32 v[180:181], v[248:249], v[248:249], v[180:181]
	s_waitcnt lgkmcnt(1)
	v_pk_fma_f32 v[178:179], v[250:251], v[250:251], v[178:179]
	s_waitcnt lgkmcnt(0)
	v_pk_fma_f32 v[180:181], v[252:253], v[252:253], v[180:181]
	s_nop 0
	v_pk_add_f32 v[178:179], v[178:179], v[180:181]
	s_nop 0
	v_add_f32_e32 v178, v178, v179
	s_nop 1
	v_add_f32_dpp v178, v178, v178 quad_perm:[1,0,3,2] row_mask:0xf bank_mask:0xf bound_ctrl:1
	v_fmamk_f32 v178, v178, 0x3c000000, v209
	v_mul_f32_e32 v179, 0x4b800000, v178
	v_cmp_gt_f32_e32 vcc, s52, v178
	s_nop 1
	v_cndmask_b32_e32 v178, v178, v179, vcc
	v_rsq_f32_e32 v178, v178
	s_nop 0
	v_mul_f32_e32 v179, 0x45800000, v178
	v_cndmask_b32_e32 v178, v178, v179, vcc
	v_mov_b32_e32 v185, v134
	ds_read2_b32 v[186:187], v185 offset1:1
	ds_read2_b32 v[188:189], v185 offset0:129 offset1:130
	v_add_u32_e32 v185, 0x408, v185
	ds_read2_b32 v[190:191], v185 offset1:1
	ds_read2_b32 v[192:193], v185 offset0:129 offset1:130
	v_add_u32_e32 v185, 0x408, v185
	s_nop 0
	v_readlane_b32 s6, v178, 0
	v_readlane_b32 s100, v178, 2
	ds_read2_b32 v[194:195], v185 offset1:1
	ds_read2_b32 v[196:197], v185 offset0:129 offset1:130
	v_add_u32_e32 v185, 0x408, v185
	s_waitcnt lgkmcnt(4)
	v_pk_mul_f32 v[186:187], v[186:187], s[6:7] op_sel_hi:[1,0]
	v_pk_mul_f32 v[188:189], v[188:189], s[100:101] op_sel_hi:[1,0]
	v_readlane_b32 vcc_lo, v178, 4
	v_readlane_b32 s6, v178, 6
	v_pk_mul_f32 v[186:187], v[130:131], v[186:187]
	v_pk_mul_f32 v[188:189], v[130:131], v[188:189]
	v_cvt_pk_bf16_f32 v202, v186, v187
	v_cvt_pk_bf16_f32 v203, v188, v189
	global_store_dword v[132:133], v202, off
	v_lshl_add_u64 v[132:133], v[132:133], 0, s[82:83]
	global_store_dword v[132:133], v203, off
	v_lshl_add_u64 v[132:133], v[132:133], 0, s[82:83]
	ds_read2_b32 v[198:199], v185 offset1:1
	ds_read2_b32 v[200:201], v185 offset0:129 offset1:130
	v_add_u32_e32 v185, 0x408, v185
	s_waitcnt lgkmcnt(4)
	v_pk_mul_f32 v[190:191], v[190:191], vcc op_sel_hi:[1,0]
	v_pk_mul_f32 v[192:193], v[192:193], s[6:7] op_sel_hi:[1,0]
	v_readlane_b32 s100, v178, 8
	v_readlane_b32 vcc_lo, v178, 10
	v_pk_mul_f32 v[190:191], v[130:131], v[190:191]
	v_pk_mul_f32 v[192:193], v[130:131], v[192:193]
	v_cvt_pk_bf16_f32 v202, v190, v191
	v_cvt_pk_bf16_f32 v203, v192, v193
	global_store_dword v[132:133], v202, off
	v_lshl_add_u64 v[132:133], v[132:133], 0, s[82:83]
	global_store_dword v[132:133], v203, off
	v_lshl_add_u64 v[132:133], v[132:133], 0, s[82:83]
	ds_read2_b32 v[186:187], v185 offset1:1
	ds_read2_b32 v[188:189], v185 offset0:129 offset1:130
	v_add_u32_e32 v185, 0x408, v185
	s_waitcnt lgkmcnt(4)
	v_pk_mul_f32 v[194:195], v[194:195], s[100:101] op_sel_hi:[1,0]
	v_pk_mul_f32 v[196:197], v[196:197], vcc op_sel_hi:[1,0]
	v_readlane_b32 s6, v178, 12
	v_readlane_b32 s100, v178, 14
	v_pk_mul_f32 v[194:195], v[130:131], v[194:195]
	v_pk_mul_f32 v[196:197], v[130:131], v[196:197]
	v_cvt_pk_bf16_f32 v202, v194, v195
	v_cvt_pk_bf16_f32 v203, v196, v197
	global_store_dword v[132:133], v202, off
	v_lshl_add_u64 v[132:133], v[132:133], 0, s[82:83]
	global_store_dword v[132:133], v203, off
	v_lshl_add_u64 v[132:133], v[132:133], 0, s[82:83]
	ds_read2_b32 v[190:191], v185 offset1:1
	ds_read2_b32 v[192:193], v185 offset0:129 offset1:130
	v_add_u32_e32 v185, 0x408, v185
	s_waitcnt lgkmcnt(4)
	v_pk_mul_f32 v[198:199], v[198:199], s[6:7] op_sel_hi:[1,0]
	v_pk_mul_f32 v[200:201], v[200:201], s[100:101] op_sel_hi:[1,0]
	v_readlane_b32 vcc_lo, v178, 16
	v_readlane_b32 s6, v178, 18
	v_pk_mul_f32 v[198:199], v[130:131], v[198:199]
	v_pk_mul_f32 v[200:201], v[130:131], v[200:201]
	v_cvt_pk_bf16_f32 v202, v198, v199
	v_cvt_pk_bf16_f32 v203, v200, v201
	global_store_dword v[132:133], v202, off
	v_lshl_add_u64 v[132:133], v[132:133], 0, s[82:83]
	global_store_dword v[132:133], v203, off
	v_lshl_add_u64 v[132:133], v[132:133], 0, s[82:83]
	ds_read2_b32 v[194:195], v185 offset1:1
	ds_read2_b32 v[196:197], v185 offset0:129 offset1:130
	v_add_u32_e32 v185, 0x408, v185
	s_waitcnt lgkmcnt(4)
	v_pk_mul_f32 v[186:187], v[186:187], vcc op_sel_hi:[1,0]
	v_pk_mul_f32 v[188:189], v[188:189], s[6:7] op_sel_hi:[1,0]
	v_readlane_b32 s100, v178, 20
	v_readlane_b32 vcc_lo, v178, 22
	v_pk_mul_f32 v[186:187], v[130:131], v[186:187]
	v_pk_mul_f32 v[188:189], v[130:131], v[188:189]
	v_cvt_pk_bf16_f32 v202, v186, v187
	v_cvt_pk_bf16_f32 v203, v188, v189
	global_store_dword v[132:133], v202, off
	v_lshl_add_u64 v[132:133], v[132:133], 0, s[82:83]
	global_store_dword v[132:133], v203, off
	v_lshl_add_u64 v[132:133], v[132:133], 0, s[82:83]
	ds_read2_b32 v[198:199], v185 offset1:1
	ds_read2_b32 v[200:201], v185 offset0:129 offset1:130
	v_add_u32_e32 v185, 0x408, v185
	s_waitcnt lgkmcnt(4)
	v_pk_mul_f32 v[190:191], v[190:191], s[100:101] op_sel_hi:[1,0]
	v_pk_mul_f32 v[192:193], v[192:193], vcc op_sel_hi:[1,0]
	v_readlane_b32 s6, v178, 24
	v_readlane_b32 s100, v178, 26
	v_pk_mul_f32 v[190:191], v[130:131], v[190:191]
	v_pk_mul_f32 v[192:193], v[130:131], v[192:193]
	v_cvt_pk_bf16_f32 v202, v190, v191
	v_cvt_pk_bf16_f32 v203, v192, v193
	global_store_dword v[132:133], v202, off
	v_lshl_add_u64 v[132:133], v[132:133], 0, s[82:83]
	global_store_dword v[132:133], v203, off
	v_lshl_add_u64 v[132:133], v[132:133], 0, s[82:83]
	ds_read2_b32 v[186:187], v185 offset1:1
	ds_read2_b32 v[188:189], v185 offset0:129 offset1:130
	v_add_u32_e32 v185, 0x408, v185
	s_waitcnt lgkmcnt(4)
	v_pk_mul_f32 v[194:195], v[194:195], s[6:7] op_sel_hi:[1,0]
	v_pk_mul_f32 v[196:197], v[196:197], s[100:101] op_sel_hi:[1,0]
	v_readlane_b32 vcc_lo, v178, 28
	v_readlane_b32 s6, v178, 30
	v_pk_mul_f32 v[194:195], v[130:131], v[194:195]
	v_pk_mul_f32 v[196:197], v[130:131], v[196:197]
	v_cvt_pk_bf16_f32 v202, v194, v195
	v_cvt_pk_bf16_f32 v203, v196, v197
	global_store_dword v[132:133], v202, off
	v_lshl_add_u64 v[132:133], v[132:133], 0, s[82:83]
	global_store_dword v[132:133], v203, off
	v_lshl_add_u64 v[132:133], v[132:133], 0, s[82:83]
	ds_read2_b32 v[190:191], v185 offset1:1
	ds_read2_b32 v[192:193], v185 offset0:129 offset1:130
	v_add_u32_e32 v185, 0x408, v185
	s_waitcnt lgkmcnt(4)
	v_pk_mul_f32 v[198:199], v[198:199], vcc op_sel_hi:[1,0]
	v_pk_mul_f32 v[200:201], v[200:201], s[6:7] op_sel_hi:[1,0]
	v_readlane_b32 s100, v178, 32
	v_readlane_b32 vcc_lo, v178, 34
	v_pk_mul_f32 v[198:199], v[130:131], v[198:199]
	v_pk_mul_f32 v[200:201], v[130:131], v[200:201]
	v_cvt_pk_bf16_f32 v202, v198, v199
	v_cvt_pk_bf16_f32 v203, v200, v201
	global_store_dword v[132:133], v202, off
	v_lshl_add_u64 v[132:133], v[132:133], 0, s[82:83]
	global_store_dword v[132:133], v203, off
	v_lshl_add_u64 v[132:133], v[132:133], 0, s[82:83]
	ds_read2_b32 v[194:195], v185 offset1:1
	ds_read2_b32 v[196:197], v185 offset0:129 offset1:130
	v_add_u32_e32 v185, 0x408, v185
	s_waitcnt lgkmcnt(4)
	v_pk_mul_f32 v[186:187], v[186:187], s[100:101] op_sel_hi:[1,0]
	v_pk_mul_f32 v[188:189], v[188:189], vcc op_sel_hi:[1,0]
	v_readlane_b32 s6, v178, 36
	v_readlane_b32 s100, v178, 38
	v_pk_mul_f32 v[186:187], v[130:131], v[186:187]
	v_pk_mul_f32 v[188:189], v[130:131], v[188:189]
	v_cvt_pk_bf16_f32 v202, v186, v187
	v_cvt_pk_bf16_f32 v203, v188, v189
	global_store_dword v[132:133], v202, off
	v_lshl_add_u64 v[132:133], v[132:133], 0, s[82:83]
	global_store_dword v[132:133], v203, off
	v_lshl_add_u64 v[132:133], v[132:133], 0, s[82:83]
	ds_read2_b32 v[198:199], v185 offset1:1
	ds_read2_b32 v[200:201], v185 offset0:129 offset1:130
	v_add_u32_e32 v185, 0x408, v185
	s_waitcnt lgkmcnt(4)
	v_pk_mul_f32 v[190:191], v[190:191], s[6:7] op_sel_hi:[1,0]
	v_pk_mul_f32 v[192:193], v[192:193], s[100:101] op_sel_hi:[1,0]
	v_readlane_b32 vcc_lo, v178, 40
	v_readlane_b32 s6, v178, 42
	v_pk_mul_f32 v[190:191], v[130:131], v[190:191]
	v_pk_mul_f32 v[192:193], v[130:131], v[192:193]
	v_cvt_pk_bf16_f32 v202, v190, v191
	v_cvt_pk_bf16_f32 v203, v192, v193
	global_store_dword v[132:133], v202, off
	v_lshl_add_u64 v[132:133], v[132:133], 0, s[82:83]
	global_store_dword v[132:133], v203, off
	v_lshl_add_u64 v[132:133], v[132:133], 0, s[82:83]
	ds_read2_b32 v[186:187], v185 offset1:1
	ds_read2_b32 v[188:189], v185 offset0:129 offset1:130
	v_add_u32_e32 v185, 0x408, v185
	s_waitcnt lgkmcnt(4)
	v_pk_mul_f32 v[194:195], v[194:195], vcc op_sel_hi:[1,0]
	v_pk_mul_f32 v[196:197], v[196:197], s[6:7] op_sel_hi:[1,0]
	v_readlane_b32 s100, v178, 44
	v_readlane_b32 vcc_lo, v178, 46
	v_pk_mul_f32 v[194:195], v[130:131], v[194:195]
	v_pk_mul_f32 v[196:197], v[130:131], v[196:197]
	v_cvt_pk_bf16_f32 v202, v194, v195
	v_cvt_pk_bf16_f32 v203, v196, v197
	global_store_dword v[132:133], v202, off
	v_lshl_add_u64 v[132:133], v[132:133], 0, s[82:83]
	global_store_dword v[132:133], v203, off
	v_lshl_add_u64 v[132:133], v[132:133], 0, s[82:83]
	ds_read2_b32 v[190:191], v185 offset1:1
	ds_read2_b32 v[192:193], v185 offset0:129 offset1:130
	v_add_u32_e32 v185, 0x408, v185
	s_waitcnt lgkmcnt(4)
	v_pk_mul_f32 v[198:199], v[198:199], s[100:101] op_sel_hi:[1,0]
	v_pk_mul_f32 v[200:201], v[200:201], vcc op_sel_hi:[1,0]
	v_readlane_b32 s6, v178, 48
	v_readlane_b32 s100, v178, 50
	v_pk_mul_f32 v[198:199], v[130:131], v[198:199]
	v_pk_mul_f32 v[200:201], v[130:131], v[200:201]
	v_cvt_pk_bf16_f32 v202, v198, v199
	v_cvt_pk_bf16_f32 v203, v200, v201
	global_store_dword v[132:133], v202, off
	v_lshl_add_u64 v[132:133], v[132:133], 0, s[82:83]
	global_store_dword v[132:133], v203, off
	v_lshl_add_u64 v[132:133], v[132:133], 0, s[82:83]
	ds_read2_b32 v[194:195], v185 offset1:1
	ds_read2_b32 v[196:197], v185 offset0:129 offset1:130
	v_add_u32_e32 v185, 0x408, v185
	s_waitcnt lgkmcnt(4)
	v_pk_mul_f32 v[186:187], v[186:187], s[6:7] op_sel_hi:[1,0]
	v_pk_mul_f32 v[188:189], v[188:189], s[100:101] op_sel_hi:[1,0]
	v_readlane_b32 vcc_lo, v178, 52
	v_readlane_b32 s6, v178, 54
	v_pk_mul_f32 v[186:187], v[130:131], v[186:187]
	v_pk_mul_f32 v[188:189], v[130:131], v[188:189]
	v_cvt_pk_bf16_f32 v202, v186, v187
	v_cvt_pk_bf16_f32 v203, v188, v189
	global_store_dword v[132:133], v202, off
	v_lshl_add_u64 v[132:133], v[132:133], 0, s[82:83]
	global_store_dword v[132:133], v203, off
	v_lshl_add_u64 v[132:133], v[132:133], 0, s[82:83]
	ds_read2_b32 v[198:199], v185 offset1:1
	ds_read2_b32 v[200:201], v185 offset0:129 offset1:130
	v_add_u32_e32 v185, 0x408, v185
	s_waitcnt lgkmcnt(4)
	v_pk_mul_f32 v[190:191], v[190:191], vcc op_sel_hi:[1,0]
	v_pk_mul_f32 v[192:193], v[192:193], s[6:7] op_sel_hi:[1,0]
	v_readlane_b32 s100, v178, 56
	v_readlane_b32 vcc_lo, v178, 58
	v_pk_mul_f32 v[190:191], v[130:131], v[190:191]
	v_pk_mul_f32 v[192:193], v[130:131], v[192:193]
	v_cvt_pk_bf16_f32 v202, v190, v191
	v_cvt_pk_bf16_f32 v203, v192, v193
	global_store_dword v[132:133], v202, off
	v_lshl_add_u64 v[132:133], v[132:133], 0, s[82:83]
	global_store_dword v[132:133], v203, off
	v_lshl_add_u64 v[132:133], v[132:133], 0, s[82:83]
	s_waitcnt lgkmcnt(2)
	v_pk_mul_f32 v[194:195], v[194:195], s[100:101] op_sel_hi:[1,0]
	v_pk_mul_f32 v[196:197], v[196:197], vcc op_sel_hi:[1,0]
	v_readlane_b32 s6, v178, 60
	v_readlane_b32 s100, v178, 62
	v_pk_mul_f32 v[194:195], v[130:131], v[194:195]
	v_pk_mul_f32 v[196:197], v[130:131], v[196:197]
	v_cvt_pk_bf16_f32 v202, v194, v195
	v_cvt_pk_bf16_f32 v203, v196, v197
	global_store_dword v[132:133], v202, off
	v_lshl_add_u64 v[132:133], v[132:133], 0, s[82:83]
	global_store_dword v[132:133], v203, off
	v_lshl_add_u64 v[132:133], v[132:133], 0, s[82:83]
	s_waitcnt lgkmcnt(0)
	v_pk_mul_f32 v[198:199], v[198:199], s[6:7] op_sel_hi:[1,0]
	v_pk_mul_f32 v[200:201], v[200:201], s[100:101] op_sel_hi:[1,0]
	s_nop 1
	v_pk_mul_f32 v[198:199], v[130:131], v[198:199]
	v_pk_mul_f32 v[200:201], v[130:131], v[200:201]
	v_cvt_pk_bf16_f32 v202, v198, v199
	v_cvt_pk_bf16_f32 v203, v200, v201
	global_store_dword v[132:133], v202, off
	v_lshl_add_u64 v[132:133], v[132:133], 0, s[82:83]
	global_store_dword v[132:133], v203, off
	v_lshl_add_u64 v[132:133], v[132:133], 0, s[82:83]
	s_movk_i32 s6, 0x4080

.LBB0_945:
	v_and_b32_e32 v183, 63, v208
	v_lshlrev_b32_e32 v182, 3, v183
	v_sub_u32_e32 v182, v134, v182
	v_lshrrev_b32_e32 v184, 1, v183
	v_and_b32_e32 v183, 1, v183
	v_mul_u32_u24_e32 v184, 0x204, v184
	v_lshl_add_u32 v184, v183, 8, v184
	v_add_u32_e32 v182, v182, v184
	v_mov_b32_e32 v178, 0
	v_mov_b32_e32 v179, 0
	v_mov_b32_e32 v180, 0
	v_mov_b32_e32 v181, 0
	ds_read2_b32 v[222:223], v182 offset0:0 offset1:1
	ds_read2_b32 v[224:225], v182 offset0:2 offset1:3
	ds_read2_b32 v[226:227], v182 offset0:4 offset1:5
	ds_read2_b32 v[228:229], v182 offset0:6 offset1:7
	ds_read2_b32 v[230:231], v182 offset0:8 offset1:9
	ds_read2_b32 v[232:233], v182 offset0:10 offset1:11
	ds_read2_b32 v[234:235], v182 offset0:12 offset1:13
	ds_read2_b32 v[236:237], v182 offset0:14 offset1:15
	ds_read2_b32 v[238:239], v182 offset0:16 offset1:17
	ds_read2_b32 v[240:241], v182 offset0:18 offset1:19
	ds_read2_b32 v[242:243], v182 offset0:20 offset1:21
	ds_read2_b32 v[244:245], v182 offset0:22 offset1:23
	s_waitcnt lgkmcnt(11)
	v_pk_fma_f32 v[178:179], v[222:223], v[222:223], v[178:179]
	ds_read2_b32 v[246:247], v182 offset0:24 offset1:25
	s_waitcnt lgkmcnt(11)
	v_pk_fma_f32 v[180:181], v[224:225], v[224:225], v[180:181]
	ds_read2_b32 v[248:249], v182 offset0:26 offset1:27
	s_waitcnt lgkmcnt(11)
	v_pk_fma_f32 v[178:179], v[226:227], v[226:227], v[178:179]
	ds_read2_b32 v[250:251], v182 offset0:28 offset1:29
	s_waitcnt lgkmcnt(11)
	v_pk_fma_f32 v[180:181], v[228:229], v[228:229], v[180:181]
	ds_read2_b32 v[252:253], v182 offset0:30 offset1:31
	s_waitcnt lgkmcnt(11)
	v_pk_fma_f32 v[178:179], v[230:231], v[230:231], v[178:179]
	ds_read2_b32 v[222:223], v182 offset0:32 offset1:33
	s_waitcnt lgkmcnt(11)
	v_pk_fma_f32 v[180:181], v[232:233], v[232:233], v[180:181]
	ds_read2_b32 v[224:225], v182 offset0:34 offset1:35
	s_waitcnt lgkmcnt(11)
	v_pk_fma_f32 v[178:179], v[234:235], v[234:235], v[178:179]
	ds_read2_b32 v[226:227], v182 offset0:36 offset1:37
	s_waitcnt lgkmcnt(11)
	v_pk_fma_f32 v[180:181], v[236:237], v[236:237], v[180:181]
	ds_read2_b32 v[228:229], v182 offset0:38 offset1:39
	s_waitcnt lgkmcnt(11)
	v_pk_fma_f32 v[178:179], v[238:239], v[238:239], v[178:179]
	ds_read2_b32 v[230:231], v182 offset0:40 offset1:41
	s_waitcnt lgkmcnt(11)
	v_pk_fma_f32 v[180:181], v[240:241], v[240:241], v[180:181]
	ds_read2_b32 v[232:233], v182 offset0:42 offset1:43
	s_waitcnt lgkmcnt(11)
	v_pk_fma_f32 v[178:179], v[242:243], v[242:243], v[178:179]
	ds_read2_b32 v[234:235], v182 offset0:44 offset1:45
	s_waitcnt lgkmcnt(11)
	v_pk_fma_f32 v[180:181], v[244:245], v[244:245], v[180:181]
	ds_read2_b32 v[236:237], v182 offset0:46 offset1:47
	s_waitcnt lgkmcnt(11)
	v_pk_fma_f32 v[178:179], v[246:247], v[246:247], v[178:179]
	ds_read2_b32 v[238:239], v182 offset0:48 offset1:49
	s_waitcnt lgkmcnt(11)
	v_pk_fma_f32 v[180:181], v[248:249], v[248:249], v[180:181]
	ds_read2_b32 v[240:241], v182 offset0:50 offset1:51
	s_waitcnt lgkmcnt(11)
	v_pk_fma_f32 v[178:179], v[250:251], v[250:251], v[178:179]
	ds_read2_b32 v[242:243], v182 offset0:52 offset1:53
	s_waitcnt lgkmcnt(11)
	v_pk_fma_f32 v[180:181], v[252:253], v[252:253], v[180:181]
	ds_read2_b32 v[244:245], v182 offset0:54 offset1:55
	s_waitcnt lgkmcnt(11)
	v_pk_fma_f32 v[178:179], v[222:223], v[222:223], v[178:179]
	ds_read2_b32 v[246:247], v182 offset0:56 offset1:57
	s_waitcnt lgkmcnt(11)
	v_pk_fma_f32 v[180:181], v[224:225], v[224:225], v[180:181]
	ds_read2_b32 v[248:249], v182 offset0:58 offset1:59
	s_waitcnt lgkmcnt(11)
	v_pk_fma_f32 v[178:179], v[226:227], v[226:227], v[178:179]
	ds_read2_b32 v[250:251], v182 offset0:60 offset1:61
	s_waitcnt lgkmcnt(11)
	v_pk_fma_f32 v[180:181], v[228:229], v[228:229], v[180:181]
	ds_read2_b32 v[252:253], v182 offset0:62 offset1:63
	s_waitcnt lgkmcnt(11)
	v_pk_fma_f32 v[178:179], v[230:231], v[230:231], v[178:179]
	s_waitcnt lgkmcnt(10)
	v_pk_fma_f32 v[180:181], v[232:233], v[232:233], v[180:181]
	s_waitcnt lgkmcnt(9)
	v_pk_fma_f32 v[178:179], v[234:235], v[234:235], v[178:179]
	s_waitcnt lgkmcnt(8)
	v_pk_fma_f32 v[180:181], v[236:237], v[236:237], v[180:181]
	s_waitcnt lgkmcnt(7)
	v_pk_fma_f32 v[178:179], v[238:239], v[238:239], v[178:179]
	s_waitcnt lgkmcnt(6)
	v_pk_fma_f32 v[180:181], v[240:241], v[240:241], v[180:181]
	s_waitcnt lgkmcnt(5)
	v_pk_fma_f32 v[178:179], v[242:243], v[242:243], v[178:179]
	s_waitcnt lgkmcnt(4)
	v_pk_fma_f32 v[180:181], v[244:245], v[244:245], v[180:181]
	s_waitcnt lgkmcnt(3)
	v_pk_fma_f32 v[178:179], v[246:247], v[246:247], v[178:179]
	s_waitcnt lgkmcnt(2)
	v_pk_fma_f32 v[180:181], v[248:249], v[248:249], v[180:181]
	s_waitcnt lgkmcnt(1)
	v_pk_fma_f32 v[178:179], v[250:251], v[250:251], v[178:179]
	s_waitcnt lgkmcnt(0)
	v_pk_fma_f32 v[180:181], v[252:253], v[252:253], v[180:181]
	s_nop 0
	v_pk_add_f32 v[178:179], v[178:179], v[180:181]
	s_nop 0
	v_add_f32_e32 v178, v178, v179
	s_nop 1
	v_add_f32_dpp v178, v178, v178 quad_perm:[1,0,3,2] row_mask:0xf bank_mask:0xf bound_ctrl:1
	v_fmamk_f32 v178, v178, 0x3c000000, v209
	v_mul_f32_e32 v179, 0x4b800000, v178
	v_cmp_gt_f32_e32 vcc, s52, v178
	s_nop 1
	v_cndmask_b32_e32 v178, v178, v179, vcc
	v_rsq_f32_e32 v178, v178
	s_nop 0
	v_mul_f32_e32 v179, 0x45800000, v178
	v_cndmask_b32_e32 v178, v178, v179, vcc
	v_mov_b32_e32 v185, v134
	ds_read2_b32 v[186:187], v185 offset1:1
	ds_read2_b32 v[188:189], v185 offset0:129 offset1:130
	v_add_u32_e32 v185, 0x408, v185
	ds_read2_b32 v[190:191], v185 offset1:1
	ds_read2_b32 v[192:193], v185 offset0:129 offset1:130
	v_add_u32_e32 v185, 0x408, v185
	s_nop 0
	v_readlane_b32 s6, v178, 0
	v_readlane_b32 s100, v178, 2
	ds_read2_b32 v[194:195], v185 offset1:1
	ds_read2_b32 v[196:197], v185 offset0:129 offset1:130
	v_add_u32_e32 v185, 0x408, v185
	s_waitcnt lgkmcnt(4)
	v_pk_mul_f32 v[186:187], v[186:187], s[6:7] op_sel_hi:[1,0]
	v_pk_mul_f32 v[188:189], v[188:189], s[100:101] op_sel_hi:[1,0]
	v_readlane_b32 vcc_lo, v178, 4
	v_readlane_b32 s6, v178, 6
	v_pk_mul_f32 v[186:187], v[130:131], v[186:187]
	v_pk_mul_f32 v[188:189], v[130:131], v[188:189]
	v_cvt_pk_bf16_f32 v202, v186, v187
	v_cvt_pk_bf16_f32 v203, v188, v189
	global_store_dword v[132:133], v202, off
	v_lshl_add_u64 v[132:133], v[132:133], 0, s[82:83]
	global_store_dword v[132:133], v203, off
	v_lshl_add_u64 v[132:133], v[132:133], 0, s[82:83]
	ds_read2_b32 v[198:199], v185 offset1:1
	ds_read2_b32 v[200:201], v185 offset0:129 offset1:130
	v_add_u32_e32 v185, 0x408, v185
	s_waitcnt lgkmcnt(4)
	v_pk_mul_f32 v[190:191], v[190:191], vcc op_sel_hi:[1,0]
	v_pk_mul_f32 v[192:193], v[192:193], s[6:7] op_sel_hi:[1,0]
	v_readlane_b32 s100, v178, 8
	v_readlane_b32 vcc_lo, v178, 10
	v_pk_mul_f32 v[190:191], v[130:131], v[190:191]
	v_pk_mul_f32 v[192:193], v[130:131], v[192:193]
	v_cvt_pk_bf16_f32 v202, v190, v191
	v_cvt_pk_bf16_f32 v203, v192, v193
	global_store_dword v[132:133], v202, off
	v_lshl_add_u64 v[132:133], v[132:133], 0, s[82:83]
	global_store_dword v[132:133], v203, off
	v_lshl_add_u64 v[132:133], v[132:133], 0, s[82:83]
	ds_read2_b32 v[186:187], v185 offset1:1
	ds_read2_b32 v[188:189], v185 offset0:129 offset1:130
	v_add_u32_e32 v185, 0x408, v185
	s_waitcnt lgkmcnt(4)
	v_pk_mul_f32 v[194:195], v[194:195], s[100:101] op_sel_hi:[1,0]
	v_pk_mul_f32 v[196:197], v[196:197], vcc op_sel_hi:[1,0]
	v_readlane_b32 s6, v178, 12
	v_readlane_b32 s100, v178, 14
	v_pk_mul_f32 v[194:195], v[130:131], v[194:195]
	v_pk_mul_f32 v[196:197], v[130:131], v[196:197]
	v_cvt_pk_bf16_f32 v202, v194, v195
	v_cvt_pk_bf16_f32 v203, v196, v197
	global_store_dword v[132:133], v202, off
	v_lshl_add_u64 v[132:133], v[132:133], 0, s[82:83]
	global_store_dword v[132:133], v203, off
	v_lshl_add_u64 v[132:133], v[132:133], 0, s[82:83]
	ds_read2_b32 v[190:191], v185 offset1:1
	ds_read2_b32 v[192:193], v185 offset0:129 offset1:130
	v_add_u32_e32 v185, 0x408, v185
	s_waitcnt lgkmcnt(4)
	v_pk_mul_f32 v[198:199], v[198:199], s[6:7] op_sel_hi:[1,0]
	v_pk_mul_f32 v[200:201], v[200:201], s[100:101] op_sel_hi:[1,0]
	v_readlane_b32 vcc_lo, v178, 16
	v_readlane_b32 s6, v178, 18
	v_pk_mul_f32 v[198:199], v[130:131], v[198:199]
	v_pk_mul_f32 v[200:201], v[130:131], v[200:201]
	v_cvt_pk_bf16_f32 v202, v198, v199
	v_cvt_pk_bf16_f32 v203, v200, v201
	global_store_dword v[132:133], v202, off
	v_lshl_add_u64 v[132:133], v[132:133], 0, s[82:83]
	global_store_dword v[132:133], v203, off
	v_lshl_add_u64 v[132:133], v[132:133], 0, s[82:83]
	ds_read2_b32 v[194:195], v185 offset1:1
	ds_read2_b32 v[196:197], v185 offset0:129 offset1:130
	v_add_u32_e32 v185, 0x408, v185
	s_waitcnt lgkmcnt(4)
	v_pk_mul_f32 v[186:187], v[186:187], vcc op_sel_hi:[1,0]
	v_pk_mul_f32 v[188:189], v[188:189], s[6:7] op_sel_hi:[1,0]
	v_readlane_b32 s100, v178, 20
	v_readlane_b32 vcc_lo, v178, 22
	v_pk_mul_f32 v[186:187], v[130:131], v[186:187]
	v_pk_mul_f32 v[188:189], v[130:131], v[188:189]
	v_cvt_pk_bf16_f32 v202, v186, v187
	v_cvt_pk_bf16_f32 v203, v188, v189
	global_store_dword v[132:133], v202, off
	v_lshl_add_u64 v[132:133], v[132:133], 0, s[82:83]
	global_store_dword v[132:133], v203, off
	v_lshl_add_u64 v[132:133], v[132:133], 0, s[82:83]
	ds_read2_b32 v[198:199], v185 offset1:1
	ds_read2_b32 v[200:201], v185 offset0:129 offset1:130
	v_add_u32_e32 v185, 0x408, v185
	s_waitcnt lgkmcnt(4)
	v_pk_mul_f32 v[190:191], v[190:191], s[100:101] op_sel_hi:[1,0]
	v_pk_mul_f32 v[192:193], v[192:193], vcc op_sel_hi:[1,0]
	v_readlane_b32 s6, v178, 24
	v_readlane_b32 s100, v178, 26
	v_pk_mul_f32 v[190:191], v[130:131], v[190:191]
	v_pk_mul_f32 v[192:193], v[130:131], v[192:193]
	v_cvt_pk_bf16_f32 v202, v190, v191
	v_cvt_pk_bf16_f32 v203, v192, v193
	global_store_dword v[132:133], v202, off
	v_lshl_add_u64 v[132:133], v[132:133], 0, s[82:83]
	global_store_dword v[132:133], v203, off
	v_lshl_add_u64 v[132:133], v[132:133], 0, s[82:83]
	ds_read2_b32 v[186:187], v185 offset1:1
	ds_read2_b32 v[188:189], v185 offset0:129 offset1:130
	v_add_u32_e32 v185, 0x408, v185
	s_waitcnt lgkmcnt(4)
	v_pk_mul_f32 v[194:195], v[194:195], s[6:7] op_sel_hi:[1,0]
	v_pk_mul_f32 v[196:197], v[196:197], s[100:101] op_sel_hi:[1,0]
	v_readlane_b32 vcc_lo, v178, 28
	v_readlane_b32 s6, v178, 30
	v_pk_mul_f32 v[194:195], v[130:131], v[194:195]
	v_pk_mul_f32 v[196:197], v[130:131], v[196:197]
	v_cvt_pk_bf16_f32 v202, v194, v195
	v_cvt_pk_bf16_f32 v203, v196, v197
	global_store_dword v[132:133], v202, off
	v_lshl_add_u64 v[132:133], v[132:133], 0, s[82:83]
	global_store_dword v[132:133], v203, off
	v_lshl_add_u64 v[132:133], v[132:133], 0, s[82:83]
	ds_read2_b32 v[190:191], v185 offset1:1
	ds_read2_b32 v[192:193], v185 offset0:129 offset1:130
	v_add_u32_e32 v185, 0x408, v185
	s_waitcnt lgkmcnt(4)
	v_pk_mul_f32 v[198:199], v[198:199], vcc op_sel_hi:[1,0]
	v_pk_mul_f32 v[200:201], v[200:201], s[6:7] op_sel_hi:[1,0]
	v_readlane_b32 s100, v178, 32
	v_readlane_b32 vcc_lo, v178, 34
	v_pk_mul_f32 v[198:199], v[130:131], v[198:199]
	v_pk_mul_f32 v[200:201], v[130:131], v[200:201]
	v_cvt_pk_bf16_f32 v202, v198, v199
	v_cvt_pk_bf16_f32 v203, v200, v201
	global_store_dword v[132:133], v202, off
	v_lshl_add_u64 v[132:133], v[132:133], 0, s[82:83]
	global_store_dword v[132:133], v203, off
	v_lshl_add_u64 v[132:133], v[132:133], 0, s[82:83]
	ds_read2_b32 v[194:195], v185 offset1:1
	ds_read2_b32 v[196:197], v185 offset0:129 offset1:130
	v_add_u32_e32 v185, 0x408, v185
	s_waitcnt lgkmcnt(4)
	v_pk_mul_f32 v[186:187], v[186:187], s[100:101] op_sel_hi:[1,0]
	v_pk_mul_f32 v[188:189], v[188:189], vcc op_sel_hi:[1,0]
	v_readlane_b32 s6, v178, 36
	v_readlane_b32 s100, v178, 38
	v_pk_mul_f32 v[186:187], v[130:131], v[186:187]
	v_pk_mul_f32 v[188:189], v[130:131], v[188:189]
	v_cvt_pk_bf16_f32 v202, v186, v187
	v_cvt_pk_bf16_f32 v203, v188, v189
	global_store_dword v[132:133], v202, off
	v_lshl_add_u64 v[132:133], v[132:133], 0, s[82:83]
	global_store_dword v[132:133], v203, off
	v_lshl_add_u64 v[132:133], v[132:133], 0, s[82:83]
	ds_read2_b32 v[198:199], v185 offset1:1
	ds_read2_b32 v[200:201], v185 offset0:129 offset1:130
	v_add_u32_e32 v185, 0x408, v185
	s_waitcnt lgkmcnt(4)
	v_pk_mul_f32 v[190:191], v[190:191], s[6:7] op_sel_hi:[1,0]
	v_pk_mul_f32 v[192:193], v[192:193], s[100:101] op_sel_hi:[1,0]
	v_readlane_b32 vcc_lo, v178, 40
	v_readlane_b32 s6, v178, 42
	v_pk_mul_f32 v[190:191], v[130:131], v[190:191]
	v_pk_mul_f32 v[192:193], v[130:131], v[192:193]
	v_cvt_pk_bf16_f32 v202, v190, v191
	v_cvt_pk_bf16_f32 v203, v192, v193
	global_store_dword v[132:133], v202, off
	v_lshl_add_u64 v[132:133], v[132:133], 0, s[82:83]
	global_store_dword v[132:133], v203, off
	v_lshl_add_u64 v[132:133], v[132:133], 0, s[82:83]
	ds_read2_b32 v[186:187], v185 offset1:1
	ds_read2_b32 v[188:189], v185 offset0:129 offset1:130
	v_add_u32_e32 v185, 0x408, v185
	s_waitcnt lgkmcnt(4)
	v_pk_mul_f32 v[194:195], v[194:195], vcc op_sel_hi:[1,0]
	v_pk_mul_f32 v[196:197], v[196:197], s[6:7] op_sel_hi:[1,0]
	v_readlane_b32 s100, v178, 44
	v_readlane_b32 vcc_lo, v178, 46
	v_pk_mul_f32 v[194:195], v[130:131], v[194:195]
	v_pk_mul_f32 v[196:197], v[130:131], v[196:197]
	v_cvt_pk_bf16_f32 v202, v194, v195
	v_cvt_pk_bf16_f32 v203, v196, v197
	global_store_dword v[132:133], v202, off
	v_lshl_add_u64 v[132:133], v[132:133], 0, s[82:83]
	global_store_dword v[132:133], v203, off
	v_lshl_add_u64 v[132:133], v[132:133], 0, s[82:83]
	ds_read2_b32 v[190:191], v185 offset1:1
	ds_read2_b32 v[192:193], v185 offset0:129 offset1:130
	v_add_u32_e32 v185, 0x408, v185
	s_waitcnt lgkmcnt(4)
	v_pk_mul_f32 v[198:199], v[198:199], s[100:101] op_sel_hi:[1,0]
	v_pk_mul_f32 v[200:201], v[200:201], vcc op_sel_hi:[1,0]
	v_readlane_b32 s6, v178, 48
	v_readlane_b32 s100, v178, 50
	v_pk_mul_f32 v[198:199], v[130:131], v[198:199]
	v_pk_mul_f32 v[200:201], v[130:131], v[200:201]
	v_cvt_pk_bf16_f32 v202, v198, v199
	v_cvt_pk_bf16_f32 v203, v200, v201
	global_store_dword v[132:133], v202, off
	v_lshl_add_u64 v[132:133], v[132:133], 0, s[82:83]
	global_store_dword v[132:133], v203, off
	v_lshl_add_u64 v[132:133], v[132:133], 0, s[82:83]
	ds_read2_b32 v[194:195], v185 offset1:1
	ds_read2_b32 v[196:197], v185 offset0:129 offset1:130
	v_add_u32_e32 v185, 0x408, v185
	s_waitcnt lgkmcnt(4)
	v_pk_mul_f32 v[186:187], v[186:187], s[6:7] op_sel_hi:[1,0]
	v_pk_mul_f32 v[188:189], v[188:189], s[100:101] op_sel_hi:[1,0]
	v_readlane_b32 vcc_lo, v178, 52
	v_readlane_b32 s6, v178, 54
	v_pk_mul_f32 v[186:187], v[130:131], v[186:187]
	v_pk_mul_f32 v[188:189], v[130:131], v[188:189]
	v_cvt_pk_bf16_f32 v202, v186, v187
	v_cvt_pk_bf16_f32 v203, v188, v189
	global_store_dword v[132:133], v202, off
	v_lshl_add_u64 v[132:133], v[132:133], 0, s[82:83]
	global_store_dword v[132:133], v203, off
	v_lshl_add_u64 v[132:133], v[132:133], 0, s[82:83]
	ds_read2_b32 v[198:199], v185 offset1:1
	ds_read2_b32 v[200:201], v185 offset0:129 offset1:130
	v_add_u32_e32 v185, 0x408, v185
	s_waitcnt lgkmcnt(4)
	v_pk_mul_f32 v[190:191], v[190:191], vcc op_sel_hi:[1,0]
	v_pk_mul_f32 v[192:193], v[192:193], s[6:7] op_sel_hi:[1,0]
	v_readlane_b32 s100, v178, 56
	v_readlane_b32 vcc_lo, v178, 58
	v_pk_mul_f32 v[190:191], v[130:131], v[190:191]
	v_pk_mul_f32 v[192:193], v[130:131], v[192:193]
	v_cvt_pk_bf16_f32 v202, v190, v191
	v_cvt_pk_bf16_f32 v203, v192, v193
	global_store_dword v[132:133], v202, off
	v_lshl_add_u64 v[132:133], v[132:133], 0, s[82:83]
	global_store_dword v[132:133], v203, off
	v_lshl_add_u64 v[132:133], v[132:133], 0, s[82:83]
	s_waitcnt lgkmcnt(2)
	v_pk_mul_f32 v[194:195], v[194:195], s[100:101] op_sel_hi:[1,0]
	v_pk_mul_f32 v[196:197], v[196:197], vcc op_sel_hi:[1,0]
	v_readlane_b32 s6, v178, 60
	v_readlane_b32 s100, v178, 62
	v_pk_mul_f32 v[194:195], v[130:131], v[194:195]
	v_pk_mul_f32 v[196:197], v[130:131], v[196:197]
	v_cvt_pk_bf16_f32 v202, v194, v195
	v_cvt_pk_bf16_f32 v203, v196, v197
	global_store_dword v[132:133], v202, off
	v_lshl_add_u64 v[132:133], v[132:133], 0, s[82:83]
	global_store_dword v[132:133], v203, off
	v_lshl_add_u64 v[132:133], v[132:133], 0, s[82:83]
	s_waitcnt lgkmcnt(0)
	v_pk_mul_f32 v[198:199], v[198:199], s[6:7] op_sel_hi:[1,0]
	v_pk_mul_f32 v[200:201], v[200:201], s[100:101] op_sel_hi:[1,0]
	s_nop 1
	v_pk_mul_f32 v[198:199], v[130:131], v[198:199]
	v_pk_mul_f32 v[200:201], v[130:131], v[200:201]
	v_cvt_pk_bf16_f32 v202, v198, v199
	v_cvt_pk_bf16_f32 v203, v200, v201
	global_store_dword v[132:133], v202, off
	v_lshl_add_u64 v[132:133], v[132:133], 0, s[82:83]
	global_store_dword v[132:133], v203, off
	v_lshl_add_u64 v[132:133], v[132:133], 0, s[82:83]
	s_movk_i32 s6, 0x4080
	s_branch .LBB0_894
